# GEMM MFMA snake order: each consecutive MFMA shares the accumulator or one operand register with its predecessor (half the accumulators take k1 before k0)
# speedup vs baseline: 1.0007x; 1.0007x over previous
; #define PG8_STAGE(bufoff, gbase, voff) do { _Pragma("unroll") for (int _i = 0; _i < 2; ++_i) \
;         __builtin_amdgcn_global_load_lds((const unsigned*)((const char*)(gbase) + (voff)[_i]), (PG8_LAS unsigned*)(lds + (bufoff) + ldsw + _i * 8192), 16, 0, 0); } while (0)
; #define PG8_LDA(dst, b, h) do { _Pragma("unroll") for (int m = 0; m < 4; ++m) _Pragma("unroll") for (int k = 0; k < 2; ++k) dst[m][k] = *(const PG8_LAS bf16x8*)(lds + PG8_SA(b, h) + aoff + m * 2048 + k * 1024); } while (0)
; #define PG8_LDB(dst, b, h) do { _Pragma("unroll") for (int n = 0; n < 2; ++n) _Pragma("unroll") for (int k = 0; k < 2; ++k) dst[n][k] = *(const PG8_LAS bf16x8*)(lds + PG8_SB(b, h) + boff + n * 2048 + k * 1024); } while (0)
; #define PG8_WAIT_V(n) asm volatile("s_waitcnt vmcnt(" #n ")" ::: "memory")
; #define PG8_WAIT_L(n) asm volatile("s_waitcnt lgkmcnt(" #n ")" ::: "memory")
; #define PG8_BAR __builtin_amdgcn_s_barrier()
; #define PG8_SCHED __builtin_amdgcn_sched_barrier(0)
; template <class Epi, class Sched, bool ALIGN_EPI = false, bool SP2 = false>
; __device__ __forceinline__ void gemm_phase(PG8_LAS unsigned char* lds, const Gemm g, const Sched& S, const Epi& E) {
;     ...
;         const bool has_next = S.next(ui + 1, nxt);
;         const char* nA = has_next ? (const char*)g.A + (size_t)nxt.pm * tstep : cA; const char* nB = has_next ? (const char*)g.Bt + (size_t)nxt.pn * tstep : cB;
;         for (int t = 0; t < nt; t += 2) {
;             const bool last = (t == nt - 2);
;             const char* a1 = cA + (size_t)(t + 1) * kstepB;
;             const char* a2 = last ? nA : cA + (size_t)(t + 2) * kstepB; const char* b2 = last ? nB : cB + (size_t)(t + 2) * kstepB;
;             const char* a3 = a2 + kstepB; const char* b3 = b2 + kstepB;
;             if (last && has_next) S.a_ready(nxt);
;             if constexpr (SP2) {
;             PG8_LDB(B0, 0, 0); PG8_LDB(B1, 0, 1); PG8_SCHED; PG8_LDA(At, 0, 0); PG8_STAGE(PG8_SA(1, 1), a1 + hstepB, voffA);
;             PG8_WAIT_V(8); PG8_WAIT_L(0); PG8_BAR; PG8_MMA(0, 0, At, B0); PG8_MMA(0, 1, At, B1); PG8_BAR; PG8_SCHED;
;             PG8_LDA(At, 0, 1); PG8_STAGE(PG8_SB(0, 0), b2, voffB); PG8_STAGE(PG8_SB(0, 1), b2 + hstepB, voffB); PG8_STAGE(PG8_SA(0, 0), a2, voffA);
;             PG8_WAIT_V(8); PG8_WAIT_L(0); PG8_BAR; PG8_MMA(1, 0, At, B0); PG8_MMA(1, 1, At, B1); PG8_BAR; PG8_SCHED;
.LBB0_193:
	s_add_i32 s84, s38, 2
	s_add_u32 s39, s36, 0x4000
	s_addc_u32 s40, s37, 0
	s_cmp_eq_u32 s31, s38
	s_cselect_b32 s42, s8, s39
	s_cselect_b32 s43, s9, s40
	s_cselect_b32 s40, s62, s78
	s_cselect_b32 s41, s63, s82
	s_add_u32 s38, s42, 0x8000
	s_addc_u32 s39, s43, 0
	s_add_i32 s90, 0, 0x10000
	s_add_i32 s64, 0, 0x14000
	v_add_u32_e32 v140, s90, v174
	v_add_u32_e32 v161, s64, v174
	ds_read_b128 v[128:131], v140
	ds_read_b128 v[132:135], v140 offset:1024
	ds_read_b128 v[136:139], v140 offset:2048
	ds_read_b128 v[140:143], v140 offset:3072
	ds_read_b128 v[144:147], v161
	ds_read_b128 v[148:151], v161 offset:1024
	ds_read_b128 v[178:181], v161 offset:2048
	ds_read_b128 v[182:185], v161 offset:3072
	v_lshl_add_u64 v[172:173], s[36:37], 0, v[168:169]
	s_add_i32 m0, s21, 0xc000
	ds_read_b128 v[186:189], v177
	ds_read_b128 v[190:193], v177 offset:1024
	ds_read_b128 v[194:197], v177 offset:2048
	ds_read_b128 v[198:201], v177 offset:3072
	ds_read_b128 v[202:205], v177 offset:4096
	ds_read_b128 v[206:209], v177 offset:5120
	ds_read_b128 v[210:213], v177 offset:6144
	ds_read_b128 v[214:217], v177 offset:7168
	global_load_lds_dwordx4 v[172:173], off
	v_lshl_add_u64 v[172:173], s[36:37], 0, v[170:171]
	s_add_i32 m0, s21, 0xe000
	s_nop 0
	global_load_lds_dwordx4 v[172:173], off
	s_waitcnt vmcnt(8)
	s_waitcnt lgkmcnt(0)
	s_barrier
	s_setprio 1
	s_waitcnt lgkmcnt(0)
	v_mfma_f32_16x16x32_bf16 v[124:127], v[128:131], v[186:189], v[124:127]
	v_mfma_f32_16x16x32_bf16 v[124:127], v[132:135], v[190:193], v[124:127]
	v_mfma_f32_16x16x32_bf16 v[120:123], v[140:143], v[190:193], v[120:123]
	v_mfma_f32_16x16x32_bf16 v[120:123], v[136:139], v[186:189], v[120:123]
	v_mfma_f32_16x16x32_bf16 v[104:107], v[136:139], v[194:197], v[104:107]
	v_mfma_f32_16x16x32_bf16 v[104:107], v[140:143], v[198:201], v[104:107]
	v_mfma_f32_16x16x32_bf16 v[108:111], v[132:135], v[198:201], v[108:111]
	v_mfma_f32_16x16x32_bf16 v[108:111], v[128:131], v[194:197], v[108:111]
	v_mfma_f32_16x16x32_bf16 v[92:95], v[128:131], v[202:205], v[92:95]
	v_mfma_f32_16x16x32_bf16 v[92:95], v[132:135], v[206:209], v[92:95]
	v_mfma_f32_16x16x32_bf16 v[88:91], v[140:143], v[206:209], v[88:91]
	v_mfma_f32_16x16x32_bf16 v[88:91], v[136:139], v[202:205], v[88:91]
	v_mfma_f32_16x16x32_bf16 v[72:75], v[136:139], v[210:213], v[72:75]
	v_mfma_f32_16x16x32_bf16 v[72:75], v[140:143], v[214:217], v[72:75]
	v_mfma_f32_16x16x32_bf16 v[76:79], v[132:135], v[214:217], v[76:79]
	v_mfma_f32_16x16x32_bf16 v[76:79], v[128:131], v[210:213], v[76:79]
	s_setprio 0
	s_setprio 1
	v_mfma_f32_16x16x32_bf16 v[116:119], v[144:147], v[186:189], v[116:119]
	v_mfma_f32_16x16x32_bf16 v[116:119], v[148:151], v[190:193], v[116:119]
	v_mfma_f32_16x16x32_bf16 v[112:115], v[182:185], v[190:193], v[112:115]
	v_mfma_f32_16x16x32_bf16 v[112:115], v[178:181], v[186:189], v[112:115]
	v_mfma_f32_16x16x32_bf16 v[96:99], v[178:181], v[194:197], v[96:99]
	v_mfma_f32_16x16x32_bf16 v[96:99], v[182:185], v[198:201], v[96:99]
	v_mfma_f32_16x16x32_bf16 v[100:103], v[148:151], v[198:201], v[100:103]
	v_mfma_f32_16x16x32_bf16 v[100:103], v[144:147], v[194:197], v[100:103]
	v_mfma_f32_16x16x32_bf16 v[84:87], v[144:147], v[202:205], v[84:87]
	v_mfma_f32_16x16x32_bf16 v[84:87], v[148:151], v[206:209], v[84:87]
	v_mfma_f32_16x16x32_bf16 v[80:83], v[182:185], v[206:209], v[80:83]
	v_mfma_f32_16x16x32_bf16 v[80:83], v[178:181], v[202:205], v[80:83]
	v_mfma_f32_16x16x32_bf16 v[64:67], v[178:181], v[210:213], v[64:67]
	v_mfma_f32_16x16x32_bf16 v[64:67], v[182:185], v[214:217], v[64:67]
	v_mfma_f32_16x16x32_bf16 v[68:71], v[148:151], v[214:217], v[68:71]
	v_mfma_f32_16x16x32_bf16 v[68:71], v[144:147], v[210:213], v[68:71]
	s_setprio 0
	s_barrier
	s_add_i32 s65, s90, s20
	v_lshl_add_u64 v[172:173], s[40:41], 0, v[156:157]
	s_mov_b32 m0, s65
	ds_read_b128 v[186:189], v177 offset:16384
	ds_read_b128 v[190:193], v177 offset:17408
	ds_read_b128 v[194:197], v177 offset:18432
	ds_read_b128 v[198:201], v177 offset:19456
	ds_read_b128 v[202:205], v177 offset:20480
	ds_read_b128 v[206:209], v177 offset:21504
	ds_read_b128 v[210:213], v177 offset:22528
	ds_read_b128 v[214:217], v177 offset:23552
	global_load_lds_dwordx4 v[172:173], off
	s_add_i32 m0, s65, 0x2000
	s_add_u32 vcc_lo, s40, 0x4000
	v_lshl_add_u64 v[172:173], s[40:41], 0, v[152:153]
	s_addc_u32 vcc_hi, s41, 0
	s_add_i32 s64, s64, s20
	global_load_lds_dwordx4 v[172:173], off
	v_lshl_add_u64 v[172:173], vcc, 0, v[156:157]
	s_mov_b32 m0, s64
	s_nop 0
	global_load_lds_dwordx4 v[172:173], off
	v_lshl_add_u64 v[172:173], vcc, 0, v[152:153]
	s_add_i32 m0, s64, 0x2000
	s_nop 0
	global_load_lds_dwordx4 v[172:173], off
	v_lshl_add_u64 v[172:173], s[42:43], 0, v[158:159]
	s_mov_b32 m0, s21
	s_nop 0
	global_load_lds_dwordx4 v[172:173], off
	v_lshl_add_u64 v[172:173], s[42:43], 0, v[154:155]
	s_mov_b32 m0, s22
	s_nop 0
	global_load_lds_dwordx4 v[172:173], off
	s_waitcnt vmcnt(8)
	s_waitcnt lgkmcnt(0)
	s_barrier
; #define PG8_STAGE(bufoff, gbase, voff) do { _Pragma("unroll") for (int _i = 0; _i < 2; ++_i) \
;         __builtin_amdgcn_global_load_lds((const unsigned*)((const char*)(gbase) + (voff)[_i]), (PG8_LAS unsigned*)(lds + (bufoff) + ldsw + _i * 8192), 16, 0, 0); } while (0)
; #define PG8_LDA(dst, b, h) do { _Pragma("unroll") for (int m = 0; m < 4; ++m) _Pragma("unroll") for (int k = 0; k < 2; ++k) dst[m][k] = *(const PG8_LAS bf16x8*)(lds + PG8_SA(b, h) + aoff + m * 2048 + k * 1024); } while (0)
; #define PG8_LDB(dst, b, h) do { _Pragma("unroll") for (int n = 0; n < 2; ++n) _Pragma("unroll") for (int k = 0; k < 2; ++k) dst[n][k] = *(const PG8_LAS bf16x8*)(lds + PG8_SB(b, h) + boff + n * 2048 + k * 1024); } while (0)
; #define PG8_MMA(ai, bj, At, Bt) do { __builtin_amdgcn_s_setprio(1); _Pragma("unroll") for (int m = 0; m < 4; ++m) _Pragma("unroll") for (int n = 0; n < 2; ++n) _Pragma("unroll") for (int k = 0; k < 2; ++k) \
;         acc[ai][bj][m][n] = __builtin_amdgcn_mfma_f32_16x16x32_bf16(Bt[n][k], At[m][k], acc[ai][bj][m][n], 0, 0, 0); __builtin_amdgcn_s_setprio(0); } while (0)
; #define PG8_WAIT_V(n) asm volatile("s_waitcnt vmcnt(" #n ")" ::: "memory")
; #define PG8_WAIT_L(n) asm volatile("s_waitcnt lgkmcnt(" #n ")" ::: "memory")
; #define PG8_BAR __builtin_amdgcn_s_barrier()
; #define PG8_SCHED __builtin_amdgcn_sched_barrier(0)
; template <class Epi, class Sched, bool ALIGN_EPI = false, bool SP2 = false>
; __device__ __forceinline__ void gemm_phase(PG8_LAS unsigned char* lds, const Gemm g, const Sched& S, const Epi& E) {
;     ...
;             PG8_WAIT_V(8); PG8_WAIT_L(0); PG8_BAR; PG8_MMA(1, 0, At, B0); PG8_MMA(1, 1, At, B1); PG8_BAR; PG8_SCHED;
;             PG8_LDB(B0, 1, 0); PG8_LDB(B1, 1, 1); PG8_SCHED; PG8_LDA(At, 1, 0); PG8_STAGE(PG8_SA(0, 1), a2 + hstepB, voffA);
;             PG8_WAIT_V(8); PG8_WAIT_L(0); PG8_BAR; PG8_MMA(0, 0, At, B0); PG8_MMA(0, 1, At, B1); PG8_BAR; PG8_SCHED;
	s_setprio 1
	s_waitcnt lgkmcnt(0)
	v_mfma_f32_16x16x32_bf16 v[60:63], v[128:131], v[186:189], v[60:63]
	v_mfma_f32_16x16x32_bf16 v[60:63], v[132:135], v[190:193], v[60:63]
	v_mfma_f32_16x16x32_bf16 v[56:59], v[140:143], v[190:193], v[56:59]
	v_mfma_f32_16x16x32_bf16 v[56:59], v[136:139], v[186:189], v[56:59]
	v_mfma_f32_16x16x32_bf16 v[40:43], v[136:139], v[194:197], v[40:43]
	v_mfma_f32_16x16x32_bf16 v[40:43], v[140:143], v[198:201], v[40:43]
	v_mfma_f32_16x16x32_bf16 v[44:47], v[132:135], v[198:201], v[44:47]
	v_mfma_f32_16x16x32_bf16 v[44:47], v[128:131], v[194:197], v[44:47]
	v_mfma_f32_16x16x32_bf16 v[28:31], v[128:131], v[202:205], v[28:31]
	v_mfma_f32_16x16x32_bf16 v[28:31], v[132:135], v[206:209], v[28:31]
	v_mfma_f32_16x16x32_bf16 v[24:27], v[140:143], v[206:209], v[24:27]
	v_mfma_f32_16x16x32_bf16 v[24:27], v[136:139], v[202:205], v[24:27]
	v_mfma_f32_16x16x32_bf16 v[8:11], v[136:139], v[210:213], v[8:11]
	v_mfma_f32_16x16x32_bf16 v[8:11], v[140:143], v[214:217], v[8:11]
	v_mfma_f32_16x16x32_bf16 v[12:15], v[132:135], v[214:217], v[12:15]
	v_mfma_f32_16x16x32_bf16 v[12:15], v[128:131], v[210:213], v[12:15]
	s_setprio 0
	s_setprio 1
	v_mfma_f32_16x16x32_bf16 v[52:55], v[144:147], v[186:189], v[52:55]
	v_mfma_f32_16x16x32_bf16 v[52:55], v[148:151], v[190:193], v[52:55]
	v_mfma_f32_16x16x32_bf16 v[48:51], v[182:185], v[190:193], v[48:51]
	v_mfma_f32_16x16x32_bf16 v[48:51], v[178:181], v[186:189], v[48:51]
	v_mfma_f32_16x16x32_bf16 v[32:35], v[178:181], v[194:197], v[32:35]
	v_mfma_f32_16x16x32_bf16 v[32:35], v[182:185], v[198:201], v[32:35]
	v_mfma_f32_16x16x32_bf16 v[36:39], v[148:151], v[198:201], v[36:39]
	v_mfma_f32_16x16x32_bf16 v[36:39], v[144:147], v[194:197], v[36:39]
	v_mfma_f32_16x16x32_bf16 v[20:23], v[144:147], v[202:205], v[20:23]
	v_mfma_f32_16x16x32_bf16 v[20:23], v[148:151], v[206:209], v[20:23]
	v_mfma_f32_16x16x32_bf16 v[16:19], v[182:185], v[206:209], v[16:19]
	v_mfma_f32_16x16x32_bf16 v[16:19], v[178:181], v[202:205], v[16:19]
	v_mfma_f32_16x16x32_bf16 v[0:3], v[178:181], v[210:213], v[0:3]
	v_mfma_f32_16x16x32_bf16 v[0:3], v[182:185], v[214:217], v[0:3]
	v_mfma_f32_16x16x32_bf16 v[4:7], v[148:151], v[214:217], v[4:7]
	v_mfma_f32_16x16x32_bf16 v[4:7], v[144:147], v[210:213], v[4:7]
	s_setprio 0
	s_barrier
	s_add_i32 s64, 0, 0x18000
	s_add_i32 s65, 0, 0x1c000
	v_add_u32_e32 v140, s64, v174
	v_add_u32_e32 v161, s65, v174
	ds_read_b128 v[128:131], v140
	ds_read_b128 v[132:135], v140 offset:1024
	ds_read_b128 v[136:139], v140 offset:2048
	ds_read_b128 v[140:143], v140 offset:3072
	ds_read_b128 v[144:147], v161
	ds_read_b128 v[148:151], v161 offset:1024
	ds_read_b128 v[178:181], v161 offset:2048
	ds_read_b128 v[182:185], v161 offset:3072
	s_add_u32 s42, s42, 0x4000
	s_addc_u32 s43, s43, 0
	s_mov_b32 m0, s23
	v_lshl_add_u64 v[172:173], s[42:43], 0, v[158:159]
	ds_read_b128 v[186:189], v177 offset:32768
	ds_read_b128 v[190:193], v177 offset:33792
	ds_read_b128 v[194:197], v177 offset:34816
	ds_read_b128 v[198:201], v177 offset:35840
	ds_read_b128 v[202:205], v177 offset:36864
	ds_read_b128 v[206:209], v177 offset:37888
	ds_read_b128 v[210:213], v177 offset:38912
	ds_read_b128 v[214:217], v177 offset:39936
	global_load_lds_dwordx4 v[172:173], off
	v_lshl_add_u64 v[172:173], s[42:43], 0, v[154:155]
	s_mov_b32 m0, s24
	s_nop 0
	global_load_lds_dwordx4 v[172:173], off
	s_waitcnt vmcnt(8)
	s_waitcnt lgkmcnt(0)
	s_barrier
	s_setprio 1
	s_waitcnt lgkmcnt(0)
	v_mfma_f32_16x16x32_bf16 v[124:127], v[128:131], v[186:189], v[124:127]
	v_mfma_f32_16x16x32_bf16 v[124:127], v[132:135], v[190:193], v[124:127]
	v_mfma_f32_16x16x32_bf16 v[120:123], v[140:143], v[190:193], v[120:123]
	v_mfma_f32_16x16x32_bf16 v[120:123], v[136:139], v[186:189], v[120:123]
	v_mfma_f32_16x16x32_bf16 v[104:107], v[136:139], v[194:197], v[104:107]
	v_mfma_f32_16x16x32_bf16 v[104:107], v[140:143], v[198:201], v[104:107]
	v_mfma_f32_16x16x32_bf16 v[108:111], v[132:135], v[198:201], v[108:111]
	v_mfma_f32_16x16x32_bf16 v[108:111], v[128:131], v[194:197], v[108:111]
	v_mfma_f32_16x16x32_bf16 v[92:95], v[128:131], v[202:205], v[92:95]
	v_mfma_f32_16x16x32_bf16 v[92:95], v[132:135], v[206:209], v[92:95]
	v_mfma_f32_16x16x32_bf16 v[88:91], v[140:143], v[206:209], v[88:91]
	v_mfma_f32_16x16x32_bf16 v[88:91], v[136:139], v[202:205], v[88:91]
	v_mfma_f32_16x16x32_bf16 v[72:75], v[136:139], v[210:213], v[72:75]
	v_mfma_f32_16x16x32_bf16 v[72:75], v[140:143], v[214:217], v[72:75]
	v_mfma_f32_16x16x32_bf16 v[76:79], v[132:135], v[214:217], v[76:79]
	v_mfma_f32_16x16x32_bf16 v[76:79], v[128:131], v[210:213], v[76:79]
	s_setprio 0
	s_setprio 1
	v_mfma_f32_16x16x32_bf16 v[116:119], v[144:147], v[186:189], v[116:119]
	v_mfma_f32_16x16x32_bf16 v[116:119], v[148:151], v[190:193], v[116:119]
	v_mfma_f32_16x16x32_bf16 v[112:115], v[182:185], v[190:193], v[112:115]
	v_mfma_f32_16x16x32_bf16 v[112:115], v[178:181], v[186:189], v[112:115]
	v_mfma_f32_16x16x32_bf16 v[96:99], v[178:181], v[194:197], v[96:99]
	v_mfma_f32_16x16x32_bf16 v[96:99], v[182:185], v[198:201], v[96:99]
	v_mfma_f32_16x16x32_bf16 v[100:103], v[148:151], v[198:201], v[100:103]
	v_mfma_f32_16x16x32_bf16 v[100:103], v[144:147], v[194:197], v[100:103]
	v_mfma_f32_16x16x32_bf16 v[84:87], v[144:147], v[202:205], v[84:87]
	v_mfma_f32_16x16x32_bf16 v[84:87], v[148:151], v[206:209], v[84:87]
	v_mfma_f32_16x16x32_bf16 v[80:83], v[182:185], v[206:209], v[80:83]
	v_mfma_f32_16x16x32_bf16 v[80:83], v[178:181], v[202:205], v[80:83]
	v_mfma_f32_16x16x32_bf16 v[64:67], v[178:181], v[210:213], v[64:67]
	v_mfma_f32_16x16x32_bf16 v[64:67], v[182:185], v[214:217], v[64:67]
	v_mfma_f32_16x16x32_bf16 v[68:71], v[148:151], v[214:217], v[68:71]
	v_mfma_f32_16x16x32_bf16 v[68:71], v[144:147], v[210:213], v[68:71]
	s_setprio 0
	s_barrier
; #define PG8_STAGE(bufoff, gbase, voff) do { _Pragma("unroll") for (int _i = 0; _i < 2; ++_i) \
;         __builtin_amdgcn_global_load_lds((const unsigned*)((const char*)(gbase) + (voff)[_i]), (PG8_LAS unsigned*)(lds + (bufoff) + ldsw + _i * 8192), 16, 0, 0); } while (0)
; #define PG8_LDA(dst, b, h) do { _Pragma("unroll") for (int m = 0; m < 4; ++m) _Pragma("unroll") for (int k = 0; k < 2; ++k) dst[m][k] = *(const PG8_LAS bf16x8*)(lds + PG8_SA(b, h) + aoff + m * 2048 + k * 1024); } while (0)
; #define PG8_MMA(ai, bj, At, Bt) do { __builtin_amdgcn_s_setprio(1); _Pragma("unroll") for (int m = 0; m < 4; ++m) _Pragma("unroll") for (int n = 0; n < 2; ++n) _Pragma("unroll") for (int k = 0; k < 2; ++k) \
;         acc[ai][bj][m][n] = __builtin_amdgcn_mfma_f32_16x16x32_bf16(Bt[n][k], At[m][k], acc[ai][bj][m][n], 0, 0, 0); __builtin_amdgcn_s_setprio(0); } while (0)
; #define PG8_WAIT_V(n) asm volatile("s_waitcnt vmcnt(" #n ")" ::: "memory")
; #define PG8_WAIT_L(n) asm volatile("s_waitcnt lgkmcnt(" #n ")" ::: "memory")
; #define PG8_BAR __builtin_amdgcn_s_barrier()
; #define PG8_SCHED __builtin_amdgcn_sched_barrier(0)
; template <class Epi, class Sched, bool ALIGN_EPI = false, bool SP2 = false>
; __device__ __forceinline__ void gemm_phase(PG8_LAS unsigned char* lds, const Gemm g, const Sched& S, const Epi& E) {
;     ...
;         for (int t = 0; t < nt; t += 2) {
;     ...
;             PG8_LDA(At, 1, 1); PG8_STAGE(PG8_SB(1, 0), b3, voffB); PG8_STAGE(PG8_SB(1, 1), b3 + hstepB, voffB); PG8_STAGE(PG8_SA(1, 0), a3, voffA);
;             PG8_WAIT_V(8); PG8_WAIT_L(0); PG8_BAR; PG8_MMA(1, 0, At, B0); PG8_MMA(1, 1, At, B1); PG8_BAR; PG8_SCHED;
	s_add_u32 s42, s40, 0x8000
	s_addc_u32 s43, s41, 0
	s_add_i32 s64, s64, s20
	v_lshl_add_u64 v[172:173], s[42:43], 0, v[156:157]
	s_mov_b32 m0, s64
	ds_read_b128 v[186:189], v177 offset:49152
	ds_read_b128 v[190:193], v177 offset:50176
	ds_read_b128 v[194:197], v177 offset:51200
	ds_read_b128 v[198:201], v177 offset:52224
	ds_read_b128 v[202:205], v177 offset:53248
	ds_read_b128 v[206:209], v177 offset:54272
	ds_read_b128 v[210:213], v177 offset:55296
	ds_read_b128 v[214:217], v177 offset:56320
	global_load_lds_dwordx4 v[172:173], off
	s_add_i32 m0, s64, 0x2000
	s_add_u32 s40, s40, 0xc000
	v_lshl_add_u64 v[172:173], s[42:43], 0, v[152:153]
	s_addc_u32 s41, s41, 0
	s_add_i32 s42, s65, s20
	global_load_lds_dwordx4 v[172:173], off
	v_lshl_add_u64 v[172:173], s[40:41], 0, v[156:157]
	s_mov_b32 m0, s42
	s_nop 0
	global_load_lds_dwordx4 v[172:173], off
	v_lshl_add_u64 v[172:173], s[40:41], 0, v[152:153]
	s_add_i32 m0, s42, 0x2000
	s_nop 0
	global_load_lds_dwordx4 v[172:173], off
	v_lshl_add_u64 v[172:173], s[38:39], 0, v[158:159]
	s_mov_b32 m0, s29
	s_nop 0
	global_load_lds_dwordx4 v[172:173], off
	v_lshl_add_u64 v[172:173], s[38:39], 0, v[154:155]
	s_mov_b32 m0, s30
	s_nop 0
	global_load_lds_dwordx4 v[172:173], off
	s_waitcnt vmcnt(8)
	s_waitcnt lgkmcnt(0)
	s_barrier
	s_setprio 1
	s_waitcnt lgkmcnt(0)
	v_mfma_f32_16x16x32_bf16 v[60:63], v[128:131], v[186:189], v[60:63]
	v_mfma_f32_16x16x32_bf16 v[60:63], v[132:135], v[190:193], v[60:63]
	v_mfma_f32_16x16x32_bf16 v[56:59], v[140:143], v[190:193], v[56:59]
	v_mfma_f32_16x16x32_bf16 v[56:59], v[136:139], v[186:189], v[56:59]
	v_mfma_f32_16x16x32_bf16 v[40:43], v[136:139], v[194:197], v[40:43]
	v_mfma_f32_16x16x32_bf16 v[40:43], v[140:143], v[198:201], v[40:43]
	v_mfma_f32_16x16x32_bf16 v[44:47], v[132:135], v[198:201], v[44:47]
	v_mfma_f32_16x16x32_bf16 v[44:47], v[128:131], v[194:197], v[44:47]
	v_mfma_f32_16x16x32_bf16 v[28:31], v[128:131], v[202:205], v[28:31]
	v_mfma_f32_16x16x32_bf16 v[28:31], v[132:135], v[206:209], v[28:31]
	v_mfma_f32_16x16x32_bf16 v[24:27], v[140:143], v[206:209], v[24:27]
	v_mfma_f32_16x16x32_bf16 v[24:27], v[136:139], v[202:205], v[24:27]
	v_mfma_f32_16x16x32_bf16 v[8:11], v[136:139], v[210:213], v[8:11]
	v_mfma_f32_16x16x32_bf16 v[8:11], v[140:143], v[214:217], v[8:11]
	v_mfma_f32_16x16x32_bf16 v[12:15], v[132:135], v[214:217], v[12:15]
	v_mfma_f32_16x16x32_bf16 v[12:15], v[128:131], v[210:213], v[12:15]
	s_setprio 0
	s_setprio 1
	v_mfma_f32_16x16x32_bf16 v[52:55], v[144:147], v[186:189], v[52:55]
	v_mfma_f32_16x16x32_bf16 v[52:55], v[148:151], v[190:193], v[52:55]
	v_mfma_f32_16x16x32_bf16 v[48:51], v[182:185], v[190:193], v[48:51]
	v_mfma_f32_16x16x32_bf16 v[48:51], v[178:181], v[186:189], v[48:51]
	v_mfma_f32_16x16x32_bf16 v[32:35], v[178:181], v[194:197], v[32:35]
	v_mfma_f32_16x16x32_bf16 v[32:35], v[182:185], v[198:201], v[32:35]
	v_mfma_f32_16x16x32_bf16 v[36:39], v[148:151], v[198:201], v[36:39]
	v_mfma_f32_16x16x32_bf16 v[36:39], v[144:147], v[194:197], v[36:39]
	v_mfma_f32_16x16x32_bf16 v[20:23], v[144:147], v[202:205], v[20:23]
	v_mfma_f32_16x16x32_bf16 v[20:23], v[148:151], v[206:209], v[20:23]
	v_mfma_f32_16x16x32_bf16 v[16:19], v[182:185], v[206:209], v[16:19]
	v_mfma_f32_16x16x32_bf16 v[16:19], v[178:181], v[202:205], v[16:19]
	v_mfma_f32_16x16x32_bf16 v[0:3], v[178:181], v[210:213], v[0:3]
	v_mfma_f32_16x16x32_bf16 v[0:3], v[182:185], v[214:217], v[0:3]
	v_mfma_f32_16x16x32_bf16 v[4:7], v[148:151], v[214:217], v[4:7]
	v_mfma_f32_16x16x32_bf16 v[4:7], v[144:147], v[210:213], v[4:7]
	s_setprio 0
	s_barrier
	s_add_u32 s36, s36, 0x10000
	s_addc_u32 s37, s37, 0
	s_add_u32 s78, s78, 0x10000
	s_addc_u32 s82, s82, 0
	s_cmp_ge_u32 s84, s26
	s_mov_b32 s38, s84
	s_cbranch_scc0 .LBB0_193
	s_and_b64 vcc, exec, s[60:61]
	s_cbranch_vccz .LBB0_196
	s_barrier

; #define PG8_STAGE(bufoff, gbase, voff) do { _Pragma("unroll") for (int _i = 0; _i < 2; ++_i) \
;         __builtin_amdgcn_global_load_lds((const unsigned*)((const char*)(gbase) + (voff)[_i]), (PG8_LAS unsigned*)(lds + (bufoff) + ldsw + _i * 8192), 16, 0, 0); } while (0)
; #define PG8_LDA(dst, b, h) do { _Pragma("unroll") for (int m = 0; m < 4; ++m) _Pragma("unroll") for (int k = 0; k < 2; ++k) dst[m][k] = *(const PG8_LAS bf16x8*)(lds + PG8_SA(b, h) + aoff + m * 2048 + k * 1024); } while (0)
; #define PG8_LDB(dst, b, h) do { _Pragma("unroll") for (int n = 0; n < 2; ++n) _Pragma("unroll") for (int k = 0; k < 2; ++k) dst[n][k] = *(const PG8_LAS bf16x8*)(lds + PG8_SB(b, h) + boff + n * 2048 + k * 1024); } while (0)
; #define PG8_WAIT_V(n) asm volatile("s_waitcnt vmcnt(" #n ")" ::: "memory")
; #define PG8_WAIT_L(n) asm volatile("s_waitcnt lgkmcnt(" #n ")" ::: "memory")
; #define PG8_BAR __builtin_amdgcn_s_barrier()
; #define PG8_SCHED __builtin_amdgcn_sched_barrier(0)
; template <class Epi, class Sched, bool ALIGN_EPI = false, bool SP2 = false>
; __device__ __forceinline__ void gemm_phase(PG8_LAS unsigned char* lds, const Gemm g, const Sched& S, const Epi& E) {
;     ...
;         const bool has_next = S.next(ui + 1, nxt);
;         const char* nA = has_next ? (const char*)g.A + (size_t)nxt.pm * tstep : cA; const char* nB = has_next ? (const char*)g.Bt + (size_t)nxt.pn * tstep : cB;
;         for (int t = 0; t < nt; t += 2) {
;             const bool last = (t == nt - 2);
;             const char* a1 = cA + (size_t)(t + 1) * kstepB;
;             const char* a2 = last ? nA : cA + (size_t)(t + 2) * kstepB; const char* b2 = last ? nB : cB + (size_t)(t + 2) * kstepB;
;             const char* a3 = a2 + kstepB; const char* b3 = b2 + kstepB;
;             if (last && has_next) S.a_ready(nxt);
;             if constexpr (SP2) {
;             PG8_LDB(B0, 0, 0); PG8_LDB(B1, 0, 1); PG8_SCHED; PG8_LDA(At, 0, 0); PG8_STAGE(PG8_SA(1, 1), a1 + hstepB, voffA);
;             PG8_WAIT_V(8); PG8_WAIT_L(0); PG8_BAR; PG8_MMA(0, 0, At, B0); PG8_MMA(0, 1, At, B1); PG8_BAR; PG8_SCHED;
;             PG8_LDA(At, 0, 1); PG8_STAGE(PG8_SB(0, 0), b2, voffB); PG8_STAGE(PG8_SB(0, 1), b2 + hstepB, voffB); PG8_STAGE(PG8_SA(0, 0), a2, voffA);
;             PG8_WAIT_V(8); PG8_WAIT_L(0); PG8_BAR; PG8_MMA(1, 0, At, B0); PG8_MMA(1, 1, At, B1); PG8_BAR; PG8_SCHED;
.LBB0_232:
	s_add_u32 s31, s36, 0x4000
	s_addc_u32 s38, s37, 0
	s_cmp_eq_u32 s30, 28
	s_cselect_b32 s42, s26, s31
	s_cselect_b32 s43, s13, s38
	s_cselect_b32 s40, s27, s28
	s_cselect_b32 s41, s11, s29
	s_add_u32 s38, s42, 0x8000
	s_addc_u32 s39, s43, 0
	s_add_i32 s31, 0, 0x10000
	s_add_i32 s60, 0, 0x14000
	v_add_u32_e32 v152, s31, v169
	v_add_u32_e32 v175, s60, v169
	ds_read_b128 v[128:131], v152
	ds_read_b128 v[132:135], v152 offset:1024
	ds_read_b128 v[148:151], v152 offset:2048
	ds_read_b128 v[152:155], v152 offset:3072
	ds_read_b128 v[156:159], v175
	ds_read_b128 v[160:163], v175 offset:1024
	ds_read_b128 v[164:167], v175 offset:2048
	ds_read_b128 v[176:179], v175 offset:3072
	v_lshl_add_u64 v[212:213], s[36:37], 0, v[144:145]
	s_add_i32 m0, s17, 0xc000
	ds_read_b128 v[180:183], v174
	ds_read_b128 v[184:187], v174 offset:1024
	ds_read_b128 v[188:191], v174 offset:2048
	ds_read_b128 v[192:195], v174 offset:3072
	ds_read_b128 v[196:199], v174 offset:4096
	ds_read_b128 v[200:203], v174 offset:5120
	ds_read_b128 v[204:207], v174 offset:6144
	ds_read_b128 v[208:211], v174 offset:7168
	global_load_lds_dwordx4 v[212:213], off
	v_lshl_add_u64 v[212:213], s[36:37], 0, v[146:147]
	s_add_i32 m0, s17, 0xe000
	s_nop 0
	global_load_lds_dwordx4 v[212:213], off
	s_waitcnt vmcnt(8)
	s_waitcnt lgkmcnt(0)
	s_barrier
	s_setprio 1
	s_waitcnt lgkmcnt(0)
	v_mfma_f32_16x16x32_bf16 v[124:127], v[128:131], v[180:183], v[124:127]
	v_mfma_f32_16x16x32_bf16 v[124:127], v[132:135], v[184:187], v[124:127]
	v_mfma_f32_16x16x32_bf16 v[120:123], v[152:155], v[184:187], v[120:123]
	v_mfma_f32_16x16x32_bf16 v[120:123], v[148:151], v[180:183], v[120:123]
	v_mfma_f32_16x16x32_bf16 v[104:107], v[148:151], v[188:191], v[104:107]
	v_mfma_f32_16x16x32_bf16 v[104:107], v[152:155], v[192:195], v[104:107]
	v_mfma_f32_16x16x32_bf16 v[108:111], v[132:135], v[192:195], v[108:111]
	v_mfma_f32_16x16x32_bf16 v[108:111], v[128:131], v[188:191], v[108:111]
	v_mfma_f32_16x16x32_bf16 v[92:95], v[128:131], v[196:199], v[92:95]
	v_mfma_f32_16x16x32_bf16 v[92:95], v[132:135], v[200:203], v[92:95]
	v_mfma_f32_16x16x32_bf16 v[88:91], v[152:155], v[200:203], v[88:91]
	v_mfma_f32_16x16x32_bf16 v[88:91], v[148:151], v[196:199], v[88:91]
	v_mfma_f32_16x16x32_bf16 v[72:75], v[148:151], v[204:207], v[72:75]
	v_mfma_f32_16x16x32_bf16 v[72:75], v[152:155], v[208:211], v[72:75]
	v_mfma_f32_16x16x32_bf16 v[76:79], v[132:135], v[208:211], v[76:79]
	v_mfma_f32_16x16x32_bf16 v[76:79], v[128:131], v[204:207], v[76:79]
	s_setprio 0
	s_setprio 1
	v_mfma_f32_16x16x32_bf16 v[116:119], v[156:159], v[180:183], v[116:119]
	v_mfma_f32_16x16x32_bf16 v[116:119], v[160:163], v[184:187], v[116:119]
	v_mfma_f32_16x16x32_bf16 v[112:115], v[176:179], v[184:187], v[112:115]
	v_mfma_f32_16x16x32_bf16 v[112:115], v[164:167], v[180:183], v[112:115]
	v_mfma_f32_16x16x32_bf16 v[96:99], v[164:167], v[188:191], v[96:99]
	v_mfma_f32_16x16x32_bf16 v[96:99], v[176:179], v[192:195], v[96:99]
	v_mfma_f32_16x16x32_bf16 v[100:103], v[160:163], v[192:195], v[100:103]
	v_mfma_f32_16x16x32_bf16 v[100:103], v[156:159], v[188:191], v[100:103]
	v_mfma_f32_16x16x32_bf16 v[84:87], v[156:159], v[196:199], v[84:87]
	v_mfma_f32_16x16x32_bf16 v[84:87], v[160:163], v[200:203], v[84:87]
	v_mfma_f32_16x16x32_bf16 v[80:83], v[176:179], v[200:203], v[80:83]
	v_mfma_f32_16x16x32_bf16 v[80:83], v[164:167], v[196:199], v[80:83]
	v_mfma_f32_16x16x32_bf16 v[64:67], v[164:167], v[204:207], v[64:67]
	v_mfma_f32_16x16x32_bf16 v[64:67], v[176:179], v[208:211], v[64:67]
	v_mfma_f32_16x16x32_bf16 v[68:71], v[160:163], v[208:211], v[68:71]
	v_mfma_f32_16x16x32_bf16 v[68:71], v[156:159], v[204:207], v[68:71]
	s_setprio 0
	s_barrier
	s_add_i32 s31, s31, s14
	v_lshl_add_u64 v[212:213], s[40:41], 0, v[220:221]
	s_mov_b32 m0, s31
	ds_read_b128 v[180:183], v174 offset:16384
	ds_read_b128 v[184:187], v174 offset:17408
	ds_read_b128 v[188:191], v174 offset:18432
	ds_read_b128 v[192:195], v174 offset:19456
	ds_read_b128 v[196:199], v174 offset:20480
	ds_read_b128 v[200:203], v174 offset:21504
	ds_read_b128 v[204:207], v174 offset:22528
	ds_read_b128 v[208:211], v174 offset:23552
	global_load_lds_dwordx4 v[212:213], off
	s_add_i32 m0, s31, 0x2000
	s_add_u32 s44, s40, 0x4000
	v_lshl_add_u64 v[212:213], s[40:41], 0, v[136:137]
	s_addc_u32 s45, s41, 0
	s_add_i32 s31, s60, s14
	global_load_lds_dwordx4 v[212:213], off
	v_lshl_add_u64 v[212:213], s[44:45], 0, v[220:221]
	s_mov_b32 m0, s31
	s_nop 0
	global_load_lds_dwordx4 v[212:213], off
	v_lshl_add_u64 v[212:213], s[44:45], 0, v[136:137]
	s_add_i32 m0, s31, 0x2000
	s_nop 0
	global_load_lds_dwordx4 v[212:213], off
	v_lshl_add_u64 v[212:213], s[42:43], 0, v[140:141]
	s_mov_b32 m0, s17
	s_nop 0
	global_load_lds_dwordx4 v[212:213], off
	v_lshl_add_u64 v[212:213], s[42:43], 0, v[138:139]
	s_mov_b32 m0, s18
	s_nop 0
	global_load_lds_dwordx4 v[212:213], off
	s_waitcnt vmcnt(8)
	s_waitcnt lgkmcnt(0)
	s_barrier
; #define PG8_STAGE(bufoff, gbase, voff) do { _Pragma("unroll") for (int _i = 0; _i < 2; ++_i) \
;         __builtin_amdgcn_global_load_lds((const unsigned*)((const char*)(gbase) + (voff)[_i]), (PG8_LAS unsigned*)(lds + (bufoff) + ldsw + _i * 8192), 16, 0, 0); } while (0)
; #define PG8_LDA(dst, b, h) do { _Pragma("unroll") for (int m = 0; m < 4; ++m) _Pragma("unroll") for (int k = 0; k < 2; ++k) dst[m][k] = *(const PG8_LAS bf16x8*)(lds + PG8_SA(b, h) + aoff + m * 2048 + k * 1024); } while (0)
; #define PG8_LDB(dst, b, h) do { _Pragma("unroll") for (int n = 0; n < 2; ++n) _Pragma("unroll") for (int k = 0; k < 2; ++k) dst[n][k] = *(const PG8_LAS bf16x8*)(lds + PG8_SB(b, h) + boff + n * 2048 + k * 1024); } while (0)
; #define PG8_MMA(ai, bj, At, Bt) do { __builtin_amdgcn_s_setprio(1); _Pragma("unroll") for (int m = 0; m < 4; ++m) _Pragma("unroll") for (int n = 0; n < 2; ++n) _Pragma("unroll") for (int k = 0; k < 2; ++k) \
;         acc[ai][bj][m][n] = __builtin_amdgcn_mfma_f32_16x16x32_bf16(Bt[n][k], At[m][k], acc[ai][bj][m][n], 0, 0, 0); __builtin_amdgcn_s_setprio(0); } while (0)
; #define PG8_WAIT_V(n) asm volatile("s_waitcnt vmcnt(" #n ")" ::: "memory")
; #define PG8_WAIT_L(n) asm volatile("s_waitcnt lgkmcnt(" #n ")" ::: "memory")
; #define PG8_BAR __builtin_amdgcn_s_barrier()
; #define PG8_SCHED __builtin_amdgcn_sched_barrier(0)
; template <class Epi, class Sched, bool ALIGN_EPI = false, bool SP2 = false>
; __device__ __forceinline__ void gemm_phase(PG8_LAS unsigned char* lds, const Gemm g, const Sched& S, const Epi& E) {
;     ...
;             PG8_WAIT_V(8); PG8_WAIT_L(0); PG8_BAR; PG8_MMA(1, 0, At, B0); PG8_MMA(1, 1, At, B1); PG8_BAR; PG8_SCHED;
;             PG8_LDB(B0, 1, 0); PG8_LDB(B1, 1, 1); PG8_SCHED; PG8_LDA(At, 1, 0); PG8_STAGE(PG8_SA(0, 1), a2 + hstepB, voffA);
;             PG8_WAIT_V(8); PG8_WAIT_L(0); PG8_BAR; PG8_MMA(0, 0, At, B0); PG8_MMA(0, 1, At, B1); PG8_BAR; PG8_SCHED;
	s_setprio 1
	s_waitcnt lgkmcnt(0)
	v_mfma_f32_16x16x32_bf16 v[60:63], v[128:131], v[180:183], v[60:63]
	v_mfma_f32_16x16x32_bf16 v[60:63], v[132:135], v[184:187], v[60:63]
	v_mfma_f32_16x16x32_bf16 v[56:59], v[152:155], v[184:187], v[56:59]
	v_mfma_f32_16x16x32_bf16 v[56:59], v[148:151], v[180:183], v[56:59]
	v_mfma_f32_16x16x32_bf16 v[40:43], v[148:151], v[188:191], v[40:43]
	v_mfma_f32_16x16x32_bf16 v[40:43], v[152:155], v[192:195], v[40:43]
	v_mfma_f32_16x16x32_bf16 v[48:51], v[132:135], v[192:195], v[48:51]
	v_mfma_f32_16x16x32_bf16 v[48:51], v[128:131], v[188:191], v[48:51]
	v_mfma_f32_16x16x32_bf16 v[32:35], v[128:131], v[196:199], v[32:35]
	v_mfma_f32_16x16x32_bf16 v[32:35], v[132:135], v[200:203], v[32:35]
	v_mfma_f32_16x16x32_bf16 v[24:27], v[152:155], v[200:203], v[24:27]
	v_mfma_f32_16x16x32_bf16 v[24:27], v[148:151], v[196:199], v[24:27]
	v_mfma_f32_16x16x32_bf16 v[8:11], v[148:151], v[204:207], v[8:11]
	v_mfma_f32_16x16x32_bf16 v[8:11], v[152:155], v[208:211], v[8:11]
	v_mfma_f32_16x16x32_bf16 v[16:19], v[132:135], v[208:211], v[16:19]
	v_mfma_f32_16x16x32_bf16 v[16:19], v[128:131], v[204:207], v[16:19]
	s_setprio 0
	s_setprio 1
	v_mfma_f32_16x16x32_bf16 v[52:55], v[156:159], v[180:183], v[52:55]
	v_mfma_f32_16x16x32_bf16 v[52:55], v[160:163], v[184:187], v[52:55]
	v_mfma_f32_16x16x32_bf16 v[44:47], v[176:179], v[184:187], v[44:47]
	v_mfma_f32_16x16x32_bf16 v[44:47], v[164:167], v[180:183], v[44:47]
	v_mfma_f32_16x16x32_bf16 v[28:31], v[164:167], v[188:191], v[28:31]
	v_mfma_f32_16x16x32_bf16 v[28:31], v[176:179], v[192:195], v[28:31]
	v_mfma_f32_16x16x32_bf16 v[36:39], v[160:163], v[192:195], v[36:39]
	v_mfma_f32_16x16x32_bf16 v[36:39], v[156:159], v[188:191], v[36:39]
	v_mfma_f32_16x16x32_bf16 v[20:23], v[156:159], v[196:199], v[20:23]
	v_mfma_f32_16x16x32_bf16 v[20:23], v[160:163], v[200:203], v[20:23]
	v_mfma_f32_16x16x32_bf16 v[12:15], v[176:179], v[200:203], v[12:15]
	v_mfma_f32_16x16x32_bf16 v[12:15], v[164:167], v[196:199], v[12:15]
	v_mfma_f32_16x16x32_bf16 v[0:3], v[164:167], v[204:207], v[0:3]
	v_mfma_f32_16x16x32_bf16 v[0:3], v[176:179], v[208:211], v[0:3]
	v_mfma_f32_16x16x32_bf16 v[4:7], v[160:163], v[208:211], v[4:7]
	v_mfma_f32_16x16x32_bf16 v[4:7], v[156:159], v[204:207], v[4:7]
	s_setprio 0
	s_barrier
	s_add_i32 s31, 0, 0x18000
	s_add_i32 s44, 0, 0x1c000
	v_add_u32_e32 v152, s31, v169
	v_add_u32_e32 v175, s44, v169
	ds_read_b128 v[128:131], v152
	ds_read_b128 v[132:135], v152 offset:1024
	ds_read_b128 v[148:151], v152 offset:2048
	ds_read_b128 v[152:155], v152 offset:3072
	ds_read_b128 v[156:159], v175
	ds_read_b128 v[160:163], v175 offset:1024
	ds_read_b128 v[164:167], v175 offset:2048
	ds_read_b128 v[176:179], v175 offset:3072
	s_add_u32 s42, s42, 0x4000
	s_addc_u32 s43, s43, 0
	s_mov_b32 m0, s19
	v_lshl_add_u64 v[212:213], s[42:43], 0, v[140:141]
	ds_read_b128 v[180:183], v174 offset:32768
	ds_read_b128 v[184:187], v174 offset:33792
	ds_read_b128 v[188:191], v174 offset:34816
	ds_read_b128 v[192:195], v174 offset:35840
	ds_read_b128 v[196:199], v174 offset:36864
	ds_read_b128 v[200:203], v174 offset:37888
	ds_read_b128 v[204:207], v174 offset:38912
	ds_read_b128 v[208:211], v174 offset:39936
	global_load_lds_dwordx4 v[212:213], off
	v_lshl_add_u64 v[212:213], s[42:43], 0, v[138:139]
	s_mov_b32 m0, s20
	s_nop 0
	global_load_lds_dwordx4 v[212:213], off
	s_waitcnt vmcnt(8)
	s_waitcnt lgkmcnt(0)
	s_barrier
	s_setprio 1
	s_waitcnt lgkmcnt(0)
	v_mfma_f32_16x16x32_bf16 v[124:127], v[128:131], v[180:183], v[124:127]
	v_mfma_f32_16x16x32_bf16 v[124:127], v[132:135], v[184:187], v[124:127]
	v_mfma_f32_16x16x32_bf16 v[120:123], v[152:155], v[184:187], v[120:123]
	v_mfma_f32_16x16x32_bf16 v[120:123], v[148:151], v[180:183], v[120:123]
	v_mfma_f32_16x16x32_bf16 v[104:107], v[148:151], v[188:191], v[104:107]
	v_mfma_f32_16x16x32_bf16 v[104:107], v[152:155], v[192:195], v[104:107]
	v_mfma_f32_16x16x32_bf16 v[108:111], v[132:135], v[192:195], v[108:111]
	v_mfma_f32_16x16x32_bf16 v[108:111], v[128:131], v[188:191], v[108:111]
	v_mfma_f32_16x16x32_bf16 v[92:95], v[128:131], v[196:199], v[92:95]
	v_mfma_f32_16x16x32_bf16 v[92:95], v[132:135], v[200:203], v[92:95]
	v_mfma_f32_16x16x32_bf16 v[88:91], v[152:155], v[200:203], v[88:91]
	v_mfma_f32_16x16x32_bf16 v[88:91], v[148:151], v[196:199], v[88:91]
	v_mfma_f32_16x16x32_bf16 v[72:75], v[148:151], v[204:207], v[72:75]
	v_mfma_f32_16x16x32_bf16 v[72:75], v[152:155], v[208:211], v[72:75]
	v_mfma_f32_16x16x32_bf16 v[76:79], v[132:135], v[208:211], v[76:79]
	v_mfma_f32_16x16x32_bf16 v[76:79], v[128:131], v[204:207], v[76:79]
	s_setprio 0
	s_setprio 1
	v_mfma_f32_16x16x32_bf16 v[116:119], v[156:159], v[180:183], v[116:119]
	v_mfma_f32_16x16x32_bf16 v[116:119], v[160:163], v[184:187], v[116:119]
	v_mfma_f32_16x16x32_bf16 v[112:115], v[176:179], v[184:187], v[112:115]
	v_mfma_f32_16x16x32_bf16 v[112:115], v[164:167], v[180:183], v[112:115]
	v_mfma_f32_16x16x32_bf16 v[96:99], v[164:167], v[188:191], v[96:99]
	v_mfma_f32_16x16x32_bf16 v[96:99], v[176:179], v[192:195], v[96:99]
	v_mfma_f32_16x16x32_bf16 v[100:103], v[160:163], v[192:195], v[100:103]
	v_mfma_f32_16x16x32_bf16 v[100:103], v[156:159], v[188:191], v[100:103]
	v_mfma_f32_16x16x32_bf16 v[84:87], v[156:159], v[196:199], v[84:87]
	v_mfma_f32_16x16x32_bf16 v[84:87], v[160:163], v[200:203], v[84:87]
	v_mfma_f32_16x16x32_bf16 v[80:83], v[176:179], v[200:203], v[80:83]
	v_mfma_f32_16x16x32_bf16 v[80:83], v[164:167], v[196:199], v[80:83]
	v_mfma_f32_16x16x32_bf16 v[64:67], v[164:167], v[204:207], v[64:67]
	v_mfma_f32_16x16x32_bf16 v[64:67], v[176:179], v[208:211], v[64:67]
	v_mfma_f32_16x16x32_bf16 v[68:71], v[160:163], v[208:211], v[68:71]
	v_mfma_f32_16x16x32_bf16 v[68:71], v[156:159], v[204:207], v[68:71]
	s_setprio 0
	s_barrier
; #define PG8_STAGE(bufoff, gbase, voff) do { _Pragma("unroll") for (int _i = 0; _i < 2; ++_i) \
;         __builtin_amdgcn_global_load_lds((const unsigned*)((const char*)(gbase) + (voff)[_i]), (PG8_LAS unsigned*)(lds + (bufoff) + ldsw + _i * 8192), 16, 0, 0); } while (0)
; #define PG8_LDA(dst, b, h) do { _Pragma("unroll") for (int m = 0; m < 4; ++m) _Pragma("unroll") for (int k = 0; k < 2; ++k) dst[m][k] = *(const PG8_LAS bf16x8*)(lds + PG8_SA(b, h) + aoff + m * 2048 + k * 1024); } while (0)
; #define PG8_MMA(ai, bj, At, Bt) do { __builtin_amdgcn_s_setprio(1); _Pragma("unroll") for (int m = 0; m < 4; ++m) _Pragma("unroll") for (int n = 0; n < 2; ++n) _Pragma("unroll") for (int k = 0; k < 2; ++k) \
;         acc[ai][bj][m][n] = __builtin_amdgcn_mfma_f32_16x16x32_bf16(Bt[n][k], At[m][k], acc[ai][bj][m][n], 0, 0, 0); __builtin_amdgcn_s_setprio(0); } while (0)
; #define PG8_WAIT_V(n) asm volatile("s_waitcnt vmcnt(" #n ")" ::: "memory")
; #define PG8_WAIT_L(n) asm volatile("s_waitcnt lgkmcnt(" #n ")" ::: "memory")
; #define PG8_BAR __builtin_amdgcn_s_barrier()
; #define PG8_SCHED __builtin_amdgcn_sched_barrier(0)
; template <class Epi, class Sched, bool ALIGN_EPI = false, bool SP2 = false>
; __device__ __forceinline__ void gemm_phase(PG8_LAS unsigned char* lds, const Gemm g, const Sched& S, const Epi& E) {
;     ...
;         for (int t = 0; t < nt; t += 2) {
;     ...
;             PG8_LDA(At, 1, 1); PG8_STAGE(PG8_SB(1, 0), b3, voffB); PG8_STAGE(PG8_SB(1, 1), b3 + hstepB, voffB); PG8_STAGE(PG8_SA(1, 0), a3, voffA);
;             PG8_WAIT_V(8); PG8_WAIT_L(0); PG8_BAR; PG8_MMA(1, 0, At, B0); PG8_MMA(1, 1, At, B1); PG8_BAR; PG8_SCHED;
	s_add_u32 s42, s40, 0x8000
	s_addc_u32 s43, s41, 0
	s_add_i32 s31, s31, s14
	v_lshl_add_u64 v[212:213], s[42:43], 0, v[220:221]
	s_mov_b32 m0, s31
	ds_read_b128 v[180:183], v174 offset:49152
	ds_read_b128 v[184:187], v174 offset:50176
	ds_read_b128 v[188:191], v174 offset:51200
	ds_read_b128 v[192:195], v174 offset:52224
	ds_read_b128 v[196:199], v174 offset:53248
	ds_read_b128 v[200:203], v174 offset:54272
	ds_read_b128 v[204:207], v174 offset:55296
	ds_read_b128 v[208:211], v174 offset:56320
	global_load_lds_dwordx4 v[212:213], off
	s_add_i32 m0, s31, 0x2000
	s_add_u32 s40, s40, 0xc000
	v_lshl_add_u64 v[212:213], s[42:43], 0, v[136:137]
	s_addc_u32 s41, s41, 0
	s_add_i32 s31, s44, s14
	global_load_lds_dwordx4 v[212:213], off
	v_lshl_add_u64 v[212:213], s[40:41], 0, v[220:221]
	s_mov_b32 m0, s31
	s_nop 0
	global_load_lds_dwordx4 v[212:213], off
	v_lshl_add_u64 v[212:213], s[40:41], 0, v[136:137]
	s_add_i32 m0, s31, 0x2000
	s_nop 0
	global_load_lds_dwordx4 v[212:213], off
	v_lshl_add_u64 v[212:213], s[38:39], 0, v[140:141]
	s_mov_b32 m0, s21
	s_nop 0
	global_load_lds_dwordx4 v[212:213], off
	v_lshl_add_u64 v[212:213], s[38:39], 0, v[138:139]
	s_mov_b32 m0, s22
	s_nop 0
	global_load_lds_dwordx4 v[212:213], off
	s_waitcnt vmcnt(8)
	s_waitcnt lgkmcnt(0)
	s_barrier
	s_setprio 1
	s_waitcnt lgkmcnt(0)
	v_mfma_f32_16x16x32_bf16 v[60:63], v[128:131], v[180:183], v[60:63]
	v_mfma_f32_16x16x32_bf16 v[60:63], v[132:135], v[184:187], v[60:63]
	v_mfma_f32_16x16x32_bf16 v[56:59], v[152:155], v[184:187], v[56:59]
	v_mfma_f32_16x16x32_bf16 v[56:59], v[148:151], v[180:183], v[56:59]
	v_mfma_f32_16x16x32_bf16 v[40:43], v[148:151], v[188:191], v[40:43]
	v_mfma_f32_16x16x32_bf16 v[40:43], v[152:155], v[192:195], v[40:43]
	v_mfma_f32_16x16x32_bf16 v[48:51], v[132:135], v[192:195], v[48:51]
	v_mfma_f32_16x16x32_bf16 v[48:51], v[128:131], v[188:191], v[48:51]
	v_mfma_f32_16x16x32_bf16 v[32:35], v[128:131], v[196:199], v[32:35]
	v_mfma_f32_16x16x32_bf16 v[32:35], v[132:135], v[200:203], v[32:35]
	v_mfma_f32_16x16x32_bf16 v[24:27], v[152:155], v[200:203], v[24:27]
	v_mfma_f32_16x16x32_bf16 v[24:27], v[148:151], v[196:199], v[24:27]
	v_mfma_f32_16x16x32_bf16 v[8:11], v[148:151], v[204:207], v[8:11]
	v_mfma_f32_16x16x32_bf16 v[8:11], v[152:155], v[208:211], v[8:11]
	v_mfma_f32_16x16x32_bf16 v[16:19], v[132:135], v[208:211], v[16:19]
	v_mfma_f32_16x16x32_bf16 v[16:19], v[128:131], v[204:207], v[16:19]
	s_setprio 0
	s_setprio 1
	v_mfma_f32_16x16x32_bf16 v[52:55], v[156:159], v[180:183], v[52:55]
	v_mfma_f32_16x16x32_bf16 v[52:55], v[160:163], v[184:187], v[52:55]
	v_mfma_f32_16x16x32_bf16 v[44:47], v[176:179], v[184:187], v[44:47]
	v_mfma_f32_16x16x32_bf16 v[44:47], v[164:167], v[180:183], v[44:47]
	v_mfma_f32_16x16x32_bf16 v[28:31], v[164:167], v[188:191], v[28:31]
	v_mfma_f32_16x16x32_bf16 v[28:31], v[176:179], v[192:195], v[28:31]
	v_mfma_f32_16x16x32_bf16 v[36:39], v[160:163], v[192:195], v[36:39]
	v_mfma_f32_16x16x32_bf16 v[36:39], v[156:159], v[188:191], v[36:39]
	v_mfma_f32_16x16x32_bf16 v[20:23], v[156:159], v[196:199], v[20:23]
	v_mfma_f32_16x16x32_bf16 v[20:23], v[160:163], v[200:203], v[20:23]
	v_mfma_f32_16x16x32_bf16 v[12:15], v[176:179], v[200:203], v[12:15]
	v_mfma_f32_16x16x32_bf16 v[12:15], v[164:167], v[196:199], v[12:15]
	v_mfma_f32_16x16x32_bf16 v[0:3], v[164:167], v[204:207], v[0:3]
	v_mfma_f32_16x16x32_bf16 v[0:3], v[176:179], v[208:211], v[0:3]
	v_mfma_f32_16x16x32_bf16 v[4:7], v[160:163], v[208:211], v[4:7]
	v_mfma_f32_16x16x32_bf16 v[4:7], v[156:159], v[204:207], v[4:7]
	s_setprio 0
	s_barrier
	s_add_i32 s30, s30, 2
	s_add_u32 s36, s36, 0x10000
	s_addc_u32 s37, s37, 0
	s_add_u32 s28, s28, 0x10000
	s_addc_u32 s29, s29, 0
	s_cmp_gt_u32 s30, 29
	s_cbranch_scc0 .LBB0_232
	s_and_b64 vcc, exec, s[8:9]
	s_cbranch_vccz .LBB0_235
	s_barrier

; #define PG8_STAGE(bufoff, gbase, voff) do { _Pragma("unroll") for (int _i = 0; _i < 2; ++_i) \
;         __builtin_amdgcn_global_load_lds((const unsigned*)((const char*)(gbase) + (voff)[_i]), (PG8_LAS unsigned*)(lds + (bufoff) + ldsw + _i * 8192), 16, 0, 0); } while (0)
; #define PG8_LDA(dst, b, h) do { _Pragma("unroll") for (int m = 0; m < 4; ++m) _Pragma("unroll") for (int k = 0; k < 2; ++k) dst[m][k] = *(const PG8_LAS bf16x8*)(lds + PG8_SA(b, h) + aoff + m * 2048 + k * 1024); } while (0)
; #define PG8_LDB(dst, b, h) do { _Pragma("unroll") for (int n = 0; n < 2; ++n) _Pragma("unroll") for (int k = 0; k < 2; ++k) dst[n][k] = *(const PG8_LAS bf16x8*)(lds + PG8_SB(b, h) + boff + n * 2048 + k * 1024); } while (0)
; #define PG8_WAIT_V(n) asm volatile("s_waitcnt vmcnt(" #n ")" ::: "memory")
; #define PG8_WAIT_L(n) asm volatile("s_waitcnt lgkmcnt(" #n ")" ::: "memory")
; #define PG8_BAR __builtin_amdgcn_s_barrier()
; #define PG8_SCHED __builtin_amdgcn_sched_barrier(0)
; template <class Epi, class Sched, bool ALIGN_EPI = false, bool SP2 = false>
; __device__ __forceinline__ void gemm_phase(PG8_LAS unsigned char* lds, const Gemm g, const Sched& S, const Epi& E) {
;     ...
;         const bool has_next = S.next(ui + 1, nxt);
;         const char* nA = has_next ? (const char*)g.A + (size_t)nxt.pm * tstep : cA; const char* nB = has_next ? (const char*)g.Bt + (size_t)nxt.pn * tstep : cB;
;         for (int t = 0; t < nt; t += 2) {
;             const bool last = (t == nt - 2);
;             const char* a1 = cA + (size_t)(t + 1) * kstepB;
;             const char* a2 = last ? nA : cA + (size_t)(t + 2) * kstepB; const char* b2 = last ? nB : cB + (size_t)(t + 2) * kstepB;
;             const char* a3 = a2 + kstepB; const char* b3 = b2 + kstepB;
;             if (last && has_next) S.a_ready(nxt);
;             if constexpr (SP2) {
;             PG8_LDB(B0, 0, 0); PG8_LDB(B1, 0, 1); PG8_SCHED; PG8_LDA(At, 0, 0); PG8_STAGE(PG8_SA(1, 1), a1 + hstepB, voffA);
;             PG8_WAIT_V(8); PG8_WAIT_L(0); PG8_BAR; PG8_MMA(0, 0, At, B0); PG8_MMA(0, 1, At, B1); PG8_BAR; PG8_SCHED;
;             PG8_LDA(At, 0, 1); PG8_STAGE(PG8_SB(0, 0), b2, voffB); PG8_STAGE(PG8_SB(0, 1), b2 + hstepB, voffB); PG8_STAGE(PG8_SA(0, 0), a2, voffA);
;             PG8_WAIT_V(8); PG8_WAIT_L(0); PG8_BAR; PG8_MMA(1, 0, At, B0); PG8_MMA(1, 1, At, B1); PG8_BAR; PG8_SCHED;
.LBB0_263:
	s_add_u32 s38, s36, 0x4000
	s_addc_u32 s39, s37, 0
	s_cmp_eq_u32 s62, 28
	s_cselect_b32 s42, s30, s38
	s_cselect_b32 s43, s13, s39
	s_cselect_b32 s40, s31, s44
	s_cselect_b32 s41, s11, s45
	s_add_u32 s38, s42, 0x8000
	s_addc_u32 s39, s43, 0
	s_add_i32 s63, 0, 0x10000
	v_add_u32_e32 v151, s63, v165
	s_add_i32 s75, 0, 0x14000
	ds_read_b128 v[128:131], v151
	ds_read_b128 v[132:135], v151 offset:1024
	ds_read_b128 v[152:155], v151 offset:2048
	ds_read_b128 v[156:159], v151 offset:3072
	v_add_u32_e32 v151, s75, v165
	ds_read_b128 v[160:163], v151
	ds_read_b128 v[170:173], v151 offset:1024
	ds_read_b128 v[174:177], v151 offset:2048
	ds_read_b128 v[178:181], v151 offset:3072
	v_lshl_add_u64 v[214:215], s[36:37], 0, v[146:147]
	s_add_i32 m0, s19, 0xc000
	ds_read_b128 v[182:185], v168
	ds_read_b128 v[186:189], v168 offset:1024
	ds_read_b128 v[190:193], v168 offset:2048
	ds_read_b128 v[194:197], v168 offset:3072
	ds_read_b128 v[198:201], v168 offset:4096
	ds_read_b128 v[202:205], v168 offset:5120
	ds_read_b128 v[206:209], v168 offset:6144
	ds_read_b128 v[210:213], v168 offset:7168
	global_load_lds_dwordx4 v[214:215], off
	v_lshl_add_u64 v[214:215], s[36:37], 0, v[148:149]
	s_add_i32 m0, s19, 0xe000
	s_nop 0
	global_load_lds_dwordx4 v[214:215], off
	s_waitcnt vmcnt(8)
	s_waitcnt lgkmcnt(0)
	s_barrier
	s_setprio 1
	s_waitcnt lgkmcnt(0)
	v_mfma_f32_16x16x32_bf16 v[124:127], v[128:131], v[182:185], v[124:127]
	v_mfma_f32_16x16x32_bf16 v[124:127], v[132:135], v[186:189], v[124:127]
	v_mfma_f32_16x16x32_bf16 v[116:119], v[156:159], v[186:189], v[116:119]
	v_mfma_f32_16x16x32_bf16 v[116:119], v[152:155], v[182:185], v[116:119]
	v_mfma_f32_16x16x32_bf16 v[100:103], v[152:155], v[190:193], v[100:103]
	v_mfma_f32_16x16x32_bf16 v[100:103], v[156:159], v[194:197], v[100:103]
	v_mfma_f32_16x16x32_bf16 v[108:111], v[132:135], v[194:197], v[108:111]
	v_mfma_f32_16x16x32_bf16 v[108:111], v[128:131], v[190:193], v[108:111]
	v_mfma_f32_16x16x32_bf16 v[92:95], v[128:131], v[198:201], v[92:95]
	v_mfma_f32_16x16x32_bf16 v[92:95], v[132:135], v[202:205], v[92:95]
	v_mfma_f32_16x16x32_bf16 v[84:87], v[156:159], v[202:205], v[84:87]
	v_mfma_f32_16x16x32_bf16 v[84:87], v[152:155], v[198:201], v[84:87]
	v_mfma_f32_16x16x32_bf16 v[68:71], v[152:155], v[206:209], v[68:71]
	v_mfma_f32_16x16x32_bf16 v[68:71], v[156:159], v[210:213], v[68:71]
	v_mfma_f32_16x16x32_bf16 v[76:79], v[132:135], v[210:213], v[76:79]
	v_mfma_f32_16x16x32_bf16 v[76:79], v[128:131], v[206:209], v[76:79]
	s_setprio 0
	s_setprio 1
	v_mfma_f32_16x16x32_bf16 v[120:123], v[160:163], v[182:185], v[120:123]
	v_mfma_f32_16x16x32_bf16 v[120:123], v[170:173], v[186:189], v[120:123]
	v_mfma_f32_16x16x32_bf16 v[112:115], v[178:181], v[186:189], v[112:115]
	v_mfma_f32_16x16x32_bf16 v[112:115], v[174:177], v[182:185], v[112:115]
	v_mfma_f32_16x16x32_bf16 v[96:99], v[174:177], v[190:193], v[96:99]
	v_mfma_f32_16x16x32_bf16 v[96:99], v[178:181], v[194:197], v[96:99]
	v_mfma_f32_16x16x32_bf16 v[104:107], v[170:173], v[194:197], v[104:107]
	v_mfma_f32_16x16x32_bf16 v[104:107], v[160:163], v[190:193], v[104:107]
	v_mfma_f32_16x16x32_bf16 v[88:91], v[160:163], v[198:201], v[88:91]
	v_mfma_f32_16x16x32_bf16 v[88:91], v[170:173], v[202:205], v[88:91]
	v_mfma_f32_16x16x32_bf16 v[80:83], v[178:181], v[202:205], v[80:83]
	v_mfma_f32_16x16x32_bf16 v[80:83], v[174:177], v[198:201], v[80:83]
	v_mfma_f32_16x16x32_bf16 v[64:67], v[174:177], v[206:209], v[64:67]
	v_mfma_f32_16x16x32_bf16 v[64:67], v[178:181], v[210:213], v[64:67]
	v_mfma_f32_16x16x32_bf16 v[72:75], v[170:173], v[210:213], v[72:75]
	v_mfma_f32_16x16x32_bf16 v[72:75], v[160:163], v[206:209], v[72:75]
	s_setprio 0
	s_barrier
	s_add_i32 s63, s63, s16
	v_lshl_add_u64 v[214:215], s[40:41], 0, v[140:141]
	s_mov_b32 m0, s63
	ds_read_b128 v[182:185], v168 offset:16384
	ds_read_b128 v[186:189], v168 offset:17408
	ds_read_b128 v[190:193], v168 offset:18432
	ds_read_b128 v[194:197], v168 offset:19456
	ds_read_b128 v[198:201], v168 offset:20480
	ds_read_b128 v[202:205], v168 offset:21504
	ds_read_b128 v[206:209], v168 offset:22528
	ds_read_b128 v[210:213], v168 offset:23552
	global_load_lds_dwordx4 v[214:215], off
	s_add_i32 m0, s63, 0x2000
	s_add_u32 s66, s40, 0x4000
	v_lshl_add_u64 v[214:215], s[40:41], 0, v[136:137]
	s_addc_u32 s67, s41, 0
	s_add_i32 s63, s75, s16
	global_load_lds_dwordx4 v[214:215], off
	v_lshl_add_u64 v[214:215], s[66:67], 0, v[140:141]
	s_mov_b32 m0, s63
	s_nop 0
	global_load_lds_dwordx4 v[214:215], off
	v_lshl_add_u64 v[214:215], s[66:67], 0, v[136:137]
	s_add_i32 m0, s63, 0x2000
	s_nop 0
	global_load_lds_dwordx4 v[214:215], off
	v_lshl_add_u64 v[214:215], s[42:43], 0, v[142:143]
	s_mov_b32 m0, s19
	s_nop 0
	global_load_lds_dwordx4 v[214:215], off
	v_lshl_add_u64 v[214:215], s[42:43], 0, v[138:139]
	s_mov_b32 m0, s20
	s_nop 0
	global_load_lds_dwordx4 v[214:215], off
	s_waitcnt vmcnt(8)
	s_waitcnt lgkmcnt(0)
	s_barrier
; #define PG8_STAGE(bufoff, gbase, voff) do { _Pragma("unroll") for (int _i = 0; _i < 2; ++_i) \
;         __builtin_amdgcn_global_load_lds((const unsigned*)((const char*)(gbase) + (voff)[_i]), (PG8_LAS unsigned*)(lds + (bufoff) + ldsw + _i * 8192), 16, 0, 0); } while (0)
; #define PG8_LDA(dst, b, h) do { _Pragma("unroll") for (int m = 0; m < 4; ++m) _Pragma("unroll") for (int k = 0; k < 2; ++k) dst[m][k] = *(const PG8_LAS bf16x8*)(lds + PG8_SA(b, h) + aoff + m * 2048 + k * 1024); } while (0)
; #define PG8_LDB(dst, b, h) do { _Pragma("unroll") for (int n = 0; n < 2; ++n) _Pragma("unroll") for (int k = 0; k < 2; ++k) dst[n][k] = *(const PG8_LAS bf16x8*)(lds + PG8_SB(b, h) + boff + n * 2048 + k * 1024); } while (0)
; #define PG8_MMA(ai, bj, At, Bt) do { __builtin_amdgcn_s_setprio(1); _Pragma("unroll") for (int m = 0; m < 4; ++m) _Pragma("unroll") for (int n = 0; n < 2; ++n) _Pragma("unroll") for (int k = 0; k < 2; ++k) \
;         acc[ai][bj][m][n] = __builtin_amdgcn_mfma_f32_16x16x32_bf16(Bt[n][k], At[m][k], acc[ai][bj][m][n], 0, 0, 0); __builtin_amdgcn_s_setprio(0); } while (0)
; #define PG8_WAIT_V(n) asm volatile("s_waitcnt vmcnt(" #n ")" ::: "memory")
; #define PG8_WAIT_L(n) asm volatile("s_waitcnt lgkmcnt(" #n ")" ::: "memory")
; #define PG8_BAR __builtin_amdgcn_s_barrier()
; #define PG8_SCHED __builtin_amdgcn_sched_barrier(0)
; template <class Epi, class Sched, bool ALIGN_EPI = false, bool SP2 = false>
; __device__ __forceinline__ void gemm_phase(PG8_LAS unsigned char* lds, const Gemm g, const Sched& S, const Epi& E) {
;     ...
;             PG8_WAIT_V(8); PG8_WAIT_L(0); PG8_BAR; PG8_MMA(1, 0, At, B0); PG8_MMA(1, 1, At, B1); PG8_BAR; PG8_SCHED;
;             PG8_LDB(B0, 1, 0); PG8_LDB(B1, 1, 1); PG8_SCHED; PG8_LDA(At, 1, 0); PG8_STAGE(PG8_SA(0, 1), a2 + hstepB, voffA);
;             PG8_WAIT_V(8); PG8_WAIT_L(0); PG8_BAR; PG8_MMA(0, 0, At, B0); PG8_MMA(0, 1, At, B1); PG8_BAR; PG8_SCHED;
	s_setprio 1
	s_waitcnt lgkmcnt(0)
	v_mfma_f32_16x16x32_bf16 v[60:63], v[128:131], v[182:185], v[60:63]
	v_mfma_f32_16x16x32_bf16 v[60:63], v[132:135], v[186:189], v[60:63]
	v_mfma_f32_16x16x32_bf16 v[52:55], v[156:159], v[186:189], v[52:55]
	v_mfma_f32_16x16x32_bf16 v[52:55], v[152:155], v[182:185], v[52:55]
	v_mfma_f32_16x16x32_bf16 v[36:39], v[152:155], v[190:193], v[36:39]
	v_mfma_f32_16x16x32_bf16 v[36:39], v[156:159], v[194:197], v[36:39]
	v_mfma_f32_16x16x32_bf16 v[44:47], v[132:135], v[194:197], v[44:47]
	v_mfma_f32_16x16x32_bf16 v[44:47], v[128:131], v[190:193], v[44:47]
	v_mfma_f32_16x16x32_bf16 v[28:31], v[128:131], v[198:201], v[28:31]
	v_mfma_f32_16x16x32_bf16 v[28:31], v[132:135], v[202:205], v[28:31]
	v_mfma_f32_16x16x32_bf16 v[20:23], v[156:159], v[202:205], v[20:23]
	v_mfma_f32_16x16x32_bf16 v[20:23], v[152:155], v[198:201], v[20:23]
	v_mfma_f32_16x16x32_bf16 v[4:7], v[152:155], v[206:209], v[4:7]
	v_mfma_f32_16x16x32_bf16 v[4:7], v[156:159], v[210:213], v[4:7]
	v_mfma_f32_16x16x32_bf16 v[12:15], v[132:135], v[210:213], v[12:15]
	v_mfma_f32_16x16x32_bf16 v[12:15], v[128:131], v[206:209], v[12:15]
	s_setprio 0
	s_setprio 1
	v_mfma_f32_16x16x32_bf16 v[56:59], v[160:163], v[182:185], v[56:59]
	v_mfma_f32_16x16x32_bf16 v[56:59], v[170:173], v[186:189], v[56:59]
	v_mfma_f32_16x16x32_bf16 v[48:51], v[178:181], v[186:189], v[48:51]
	v_mfma_f32_16x16x32_bf16 v[48:51], v[174:177], v[182:185], v[48:51]
	v_mfma_f32_16x16x32_bf16 v[32:35], v[174:177], v[190:193], v[32:35]
	v_mfma_f32_16x16x32_bf16 v[32:35], v[178:181], v[194:197], v[32:35]
	v_mfma_f32_16x16x32_bf16 v[40:43], v[170:173], v[194:197], v[40:43]
	v_mfma_f32_16x16x32_bf16 v[40:43], v[160:163], v[190:193], v[40:43]
	v_mfma_f32_16x16x32_bf16 v[24:27], v[160:163], v[198:201], v[24:27]
	v_mfma_f32_16x16x32_bf16 v[24:27], v[170:173], v[202:205], v[24:27]
	v_mfma_f32_16x16x32_bf16 v[16:19], v[178:181], v[202:205], v[16:19]
	v_mfma_f32_16x16x32_bf16 v[16:19], v[174:177], v[198:201], v[16:19]
	v_mfma_f32_16x16x32_bf16 v[0:3], v[174:177], v[206:209], v[0:3]
	v_mfma_f32_16x16x32_bf16 v[0:3], v[178:181], v[210:213], v[0:3]
	v_mfma_f32_16x16x32_bf16 v[8:11], v[170:173], v[210:213], v[8:11]
	v_mfma_f32_16x16x32_bf16 v[8:11], v[160:163], v[206:209], v[8:11]
	s_setprio 0
	s_barrier
	s_add_i32 s63, 0, 0x18000
	v_add_u32_e32 v151, s63, v165
	s_add_i32 s66, 0, 0x1c000
	ds_read_b128 v[128:131], v151
	ds_read_b128 v[132:135], v151 offset:1024
	ds_read_b128 v[152:155], v151 offset:2048
	ds_read_b128 v[156:159], v151 offset:3072
	v_add_u32_e32 v151, s66, v165
	ds_read_b128 v[160:163], v151
	ds_read_b128 v[170:173], v151 offset:1024
	ds_read_b128 v[174:177], v151 offset:2048
	ds_read_b128 v[178:181], v151 offset:3072
	s_add_u32 s42, s42, 0x4000
	s_addc_u32 s43, s43, 0
	s_mov_b32 m0, s21
	v_lshl_add_u64 v[214:215], s[42:43], 0, v[142:143]
	ds_read_b128 v[182:185], v168 offset:32768
	ds_read_b128 v[186:189], v168 offset:33792
	ds_read_b128 v[190:193], v168 offset:34816
	ds_read_b128 v[194:197], v168 offset:35840
	ds_read_b128 v[198:201], v168 offset:36864
	ds_read_b128 v[202:205], v168 offset:37888
	ds_read_b128 v[206:209], v168 offset:38912
	ds_read_b128 v[210:213], v168 offset:39936
	global_load_lds_dwordx4 v[214:215], off
	v_lshl_add_u64 v[214:215], s[42:43], 0, v[138:139]
	s_mov_b32 m0, s22
	s_nop 0
	global_load_lds_dwordx4 v[214:215], off
	s_waitcnt vmcnt(8)
	s_waitcnt lgkmcnt(0)
	s_barrier
	s_setprio 1
	s_waitcnt lgkmcnt(0)
	v_mfma_f32_16x16x32_bf16 v[124:127], v[128:131], v[182:185], v[124:127]
	v_mfma_f32_16x16x32_bf16 v[124:127], v[132:135], v[186:189], v[124:127]
	v_mfma_f32_16x16x32_bf16 v[116:119], v[156:159], v[186:189], v[116:119]
	v_mfma_f32_16x16x32_bf16 v[116:119], v[152:155], v[182:185], v[116:119]
	v_mfma_f32_16x16x32_bf16 v[100:103], v[152:155], v[190:193], v[100:103]
	v_mfma_f32_16x16x32_bf16 v[100:103], v[156:159], v[194:197], v[100:103]
	v_mfma_f32_16x16x32_bf16 v[108:111], v[132:135], v[194:197], v[108:111]
	v_mfma_f32_16x16x32_bf16 v[108:111], v[128:131], v[190:193], v[108:111]
	v_mfma_f32_16x16x32_bf16 v[92:95], v[128:131], v[198:201], v[92:95]
	v_mfma_f32_16x16x32_bf16 v[92:95], v[132:135], v[202:205], v[92:95]
	v_mfma_f32_16x16x32_bf16 v[84:87], v[156:159], v[202:205], v[84:87]
	v_mfma_f32_16x16x32_bf16 v[84:87], v[152:155], v[198:201], v[84:87]
	v_mfma_f32_16x16x32_bf16 v[68:71], v[152:155], v[206:209], v[68:71]
	v_mfma_f32_16x16x32_bf16 v[68:71], v[156:159], v[210:213], v[68:71]
	v_mfma_f32_16x16x32_bf16 v[76:79], v[132:135], v[210:213], v[76:79]
	v_mfma_f32_16x16x32_bf16 v[76:79], v[128:131], v[206:209], v[76:79]
	s_setprio 0
	s_setprio 1
	v_mfma_f32_16x16x32_bf16 v[120:123], v[160:163], v[182:185], v[120:123]
	v_mfma_f32_16x16x32_bf16 v[120:123], v[170:173], v[186:189], v[120:123]
	v_mfma_f32_16x16x32_bf16 v[112:115], v[178:181], v[186:189], v[112:115]
	v_mfma_f32_16x16x32_bf16 v[112:115], v[174:177], v[182:185], v[112:115]
	v_mfma_f32_16x16x32_bf16 v[96:99], v[174:177], v[190:193], v[96:99]
	v_mfma_f32_16x16x32_bf16 v[96:99], v[178:181], v[194:197], v[96:99]
	v_mfma_f32_16x16x32_bf16 v[104:107], v[170:173], v[194:197], v[104:107]
	v_mfma_f32_16x16x32_bf16 v[104:107], v[160:163], v[190:193], v[104:107]
	v_mfma_f32_16x16x32_bf16 v[88:91], v[160:163], v[198:201], v[88:91]
	v_mfma_f32_16x16x32_bf16 v[88:91], v[170:173], v[202:205], v[88:91]
	v_mfma_f32_16x16x32_bf16 v[80:83], v[178:181], v[202:205], v[80:83]
	v_mfma_f32_16x16x32_bf16 v[80:83], v[174:177], v[198:201], v[80:83]
	v_mfma_f32_16x16x32_bf16 v[64:67], v[174:177], v[206:209], v[64:67]
	v_mfma_f32_16x16x32_bf16 v[64:67], v[178:181], v[210:213], v[64:67]
	v_mfma_f32_16x16x32_bf16 v[72:75], v[170:173], v[210:213], v[72:75]
	v_mfma_f32_16x16x32_bf16 v[72:75], v[160:163], v[206:209], v[72:75]
	s_setprio 0
	s_barrier
; #define PG8_STAGE(bufoff, gbase, voff) do { _Pragma("unroll") for (int _i = 0; _i < 2; ++_i) \
;         __builtin_amdgcn_global_load_lds((const unsigned*)((const char*)(gbase) + (voff)[_i]), (PG8_LAS unsigned*)(lds + (bufoff) + ldsw + _i * 8192), 16, 0, 0); } while (0)
; #define PG8_LDA(dst, b, h) do { _Pragma("unroll") for (int m = 0; m < 4; ++m) _Pragma("unroll") for (int k = 0; k < 2; ++k) dst[m][k] = *(const PG8_LAS bf16x8*)(lds + PG8_SA(b, h) + aoff + m * 2048 + k * 1024); } while (0)
; #define PG8_MMA(ai, bj, At, Bt) do { __builtin_amdgcn_s_setprio(1); _Pragma("unroll") for (int m = 0; m < 4; ++m) _Pragma("unroll") for (int n = 0; n < 2; ++n) _Pragma("unroll") for (int k = 0; k < 2; ++k) \
;         acc[ai][bj][m][n] = __builtin_amdgcn_mfma_f32_16x16x32_bf16(Bt[n][k], At[m][k], acc[ai][bj][m][n], 0, 0, 0); __builtin_amdgcn_s_setprio(0); } while (0)
; #define PG8_WAIT_V(n) asm volatile("s_waitcnt vmcnt(" #n ")" ::: "memory")
; #define PG8_WAIT_L(n) asm volatile("s_waitcnt lgkmcnt(" #n ")" ::: "memory")
; #define PG8_BAR __builtin_amdgcn_s_barrier()
; #define PG8_SCHED __builtin_amdgcn_sched_barrier(0)
; template <class Epi, class Sched, bool ALIGN_EPI = false, bool SP2 = false>
; __device__ __forceinline__ void gemm_phase(PG8_LAS unsigned char* lds, const Gemm g, const Sched& S, const Epi& E) {
;     ...
;         for (int t = 0; t < nt; t += 2) {
;     ...
;             PG8_LDA(At, 1, 1); PG8_STAGE(PG8_SB(1, 0), b3, voffB); PG8_STAGE(PG8_SB(1, 1), b3 + hstepB, voffB); PG8_STAGE(PG8_SA(1, 0), a3, voffA);
;             PG8_WAIT_V(8); PG8_WAIT_L(0); PG8_BAR; PG8_MMA(1, 0, At, B0); PG8_MMA(1, 1, At, B1); PG8_BAR; PG8_SCHED;
	s_add_u32 s42, s40, 0x8000
	s_addc_u32 s43, s41, 0
	s_add_i32 s63, s63, s16
	v_lshl_add_u64 v[214:215], s[42:43], 0, v[140:141]
	s_mov_b32 m0, s63
	ds_read_b128 v[182:185], v168 offset:49152
	ds_read_b128 v[186:189], v168 offset:50176
	ds_read_b128 v[190:193], v168 offset:51200
	ds_read_b128 v[194:197], v168 offset:52224
	ds_read_b128 v[198:201], v168 offset:53248
	ds_read_b128 v[202:205], v168 offset:54272
	ds_read_b128 v[206:209], v168 offset:55296
	ds_read_b128 v[210:213], v168 offset:56320
	global_load_lds_dwordx4 v[214:215], off
	s_add_i32 m0, s63, 0x2000
	s_add_u32 s40, s40, 0xc000
	v_lshl_add_u64 v[214:215], s[42:43], 0, v[136:137]
	s_addc_u32 s41, s41, 0
	s_add_i32 s42, s66, s16
	global_load_lds_dwordx4 v[214:215], off
	v_lshl_add_u64 v[214:215], s[40:41], 0, v[140:141]
	s_mov_b32 m0, s42
	s_nop 0
	global_load_lds_dwordx4 v[214:215], off
	v_lshl_add_u64 v[214:215], s[40:41], 0, v[136:137]
	s_add_i32 m0, s42, 0x2000
	s_nop 0
	global_load_lds_dwordx4 v[214:215], off
	v_lshl_add_u64 v[214:215], s[38:39], 0, v[142:143]
	s_mov_b32 m0, s25
	s_nop 0
	global_load_lds_dwordx4 v[214:215], off
	v_lshl_add_u64 v[214:215], s[38:39], 0, v[138:139]
	s_mov_b32 m0, s26
	s_nop 0
	global_load_lds_dwordx4 v[214:215], off
	s_waitcnt vmcnt(8)
	s_waitcnt lgkmcnt(0)
	s_barrier
	s_setprio 1
	s_waitcnt lgkmcnt(0)
	v_mfma_f32_16x16x32_bf16 v[60:63], v[128:131], v[182:185], v[60:63]
	v_mfma_f32_16x16x32_bf16 v[60:63], v[132:135], v[186:189], v[60:63]
	v_mfma_f32_16x16x32_bf16 v[52:55], v[156:159], v[186:189], v[52:55]
	v_mfma_f32_16x16x32_bf16 v[52:55], v[152:155], v[182:185], v[52:55]
	v_mfma_f32_16x16x32_bf16 v[36:39], v[152:155], v[190:193], v[36:39]
	v_mfma_f32_16x16x32_bf16 v[36:39], v[156:159], v[194:197], v[36:39]
	v_mfma_f32_16x16x32_bf16 v[44:47], v[132:135], v[194:197], v[44:47]
	v_mfma_f32_16x16x32_bf16 v[44:47], v[128:131], v[190:193], v[44:47]
	v_mfma_f32_16x16x32_bf16 v[28:31], v[128:131], v[198:201], v[28:31]
	v_mfma_f32_16x16x32_bf16 v[28:31], v[132:135], v[202:205], v[28:31]
	v_mfma_f32_16x16x32_bf16 v[20:23], v[156:159], v[202:205], v[20:23]
	v_mfma_f32_16x16x32_bf16 v[20:23], v[152:155], v[198:201], v[20:23]
	v_mfma_f32_16x16x32_bf16 v[4:7], v[152:155], v[206:209], v[4:7]
	v_mfma_f32_16x16x32_bf16 v[4:7], v[156:159], v[210:213], v[4:7]
	v_mfma_f32_16x16x32_bf16 v[12:15], v[132:135], v[210:213], v[12:15]
	v_mfma_f32_16x16x32_bf16 v[12:15], v[128:131], v[206:209], v[12:15]
	s_setprio 0
	s_setprio 1
	v_mfma_f32_16x16x32_bf16 v[56:59], v[160:163], v[182:185], v[56:59]
	v_mfma_f32_16x16x32_bf16 v[56:59], v[170:173], v[186:189], v[56:59]
	v_mfma_f32_16x16x32_bf16 v[48:51], v[178:181], v[186:189], v[48:51]
	v_mfma_f32_16x16x32_bf16 v[48:51], v[174:177], v[182:185], v[48:51]
	v_mfma_f32_16x16x32_bf16 v[32:35], v[174:177], v[190:193], v[32:35]
	v_mfma_f32_16x16x32_bf16 v[32:35], v[178:181], v[194:197], v[32:35]
	v_mfma_f32_16x16x32_bf16 v[40:43], v[170:173], v[194:197], v[40:43]
	v_mfma_f32_16x16x32_bf16 v[40:43], v[160:163], v[190:193], v[40:43]
	v_mfma_f32_16x16x32_bf16 v[24:27], v[160:163], v[198:201], v[24:27]
	v_mfma_f32_16x16x32_bf16 v[24:27], v[170:173], v[202:205], v[24:27]
	v_mfma_f32_16x16x32_bf16 v[16:19], v[178:181], v[202:205], v[16:19]
	v_mfma_f32_16x16x32_bf16 v[16:19], v[174:177], v[198:201], v[16:19]
	v_mfma_f32_16x16x32_bf16 v[0:3], v[174:177], v[206:209], v[0:3]
	v_mfma_f32_16x16x32_bf16 v[0:3], v[178:181], v[210:213], v[0:3]
	v_mfma_f32_16x16x32_bf16 v[8:11], v[170:173], v[210:213], v[8:11]
	v_mfma_f32_16x16x32_bf16 v[8:11], v[160:163], v[206:209], v[8:11]
	s_setprio 0
	s_barrier
	s_add_i32 s62, s62, 2
	s_add_u32 s36, s36, 0x10000
	s_addc_u32 s37, s37, 0
	s_add_u32 s44, s44, 0x10000
	s_addc_u32 s45, s45, 0
	s_cmp_gt_u32 s62, 29
	s_cbranch_scc0 .LBB0_263
	s_and_b64 vcc, exec, s[8:9]
	s_cbranch_vccz .LBB0_266
	s_barrier
